# short-conv in-projection K loop re-cut to 3 load/MFMA phases per K-tile (second A half in its own fragment registers, 6 barriers per K-tile); never-read pad rows of its B tile no longer fetched
# baseline (speedup 1.0000x reference)
; #define PG8_STAGE(bufoff, gbase, voff) do { const __amdgpu_buffer_rsrc_t _r = __builtin_amdgcn_make_buffer_rsrc((void*)(gbase), (short)0, 0x7fffffff, 0x00020000); _Pragma("unroll") for (int _i = 0; _i < 2; ++_i) \
;         __builtin_amdgcn_raw_ptr_buffer_load_lds(_r, (LAS unsigned*)(lds + (bufoff) + ldsw + _i * 8192), 16, (int)(voff)[_i], 0, 0, 0); } while (0)
; #define PG8_WAIT_V(n) asm volatile("s_waitcnt vmcnt(" #n ")" ::: "memory")
; #define PG8_BAR __builtin_amdgcn_s_barrier()
;     ...
;     unsigned voffA[2], voffB[2];
; #pragma unroll
;     for (int i = 0; i < 2; ++i) { int R, C; stage_rc(tid * 16 + i * 8192, R, C); voffA[i] = (unsigned)(R * lda + C) * 2u; voffB[i] = (unsigned)(R * K + C) * 2u; }
;     const size_t kstep = (size_t)(BK * 2);
;     const size_t hstepA = (size_t)HALF * lda * 2, hstepB = (size_t)HALF * K * 2;
;     const unsigned ldsw = (unsigned)wid * 1024u;
;     const int aoff = lds_byte(wr * 64 + fr, fq * 8), boff = lds_byte(wc * 32 + fr, fq * 8);
;     ...
;     PG8_STAGE(PG8_SB(0, 0), cB, voffB); PG8_STAGE(PG8_SA(0, 0), cA, voffA); PG8_STAGE(PG8_SB(0, 1), cB + hstepB, voffB); PG8_STAGE(PG8_SA(0, 1), cA + hstepA, voffA);
;     if (wr == 1) PG8_BAR;
;     PG8_WAIT_V(4); PG8_BAR;
;     PG8_STAGE(PG8_SB(1, 0), cB + kstep, voffB); PG8_STAGE(PG8_SA(1, 0), cA + kstep, voffA); PG8_STAGE(PG8_SB(1, 1), cB + hstepB + kstep, voffB);
;     PG8_WAIT_V(6); PG8_BAR;
.LBB0_834:
	v_and_b32_e32 v222, 0x80, v232
	v_cmp_ne_u32_e32 vcc, 0, v222
	v_bfrev_b32_e32 v222, 1
	v_cndmask_b32_e32 v223, v137, v222, vcc
	v_cndmask_b32_e32 v222, v135, v222, vcc
	s_lshr_b32 s7, s7, 26
	s_add_i32 s7, s6, s7
	s_ashr_i32 s80, s7, 6
	s_lshl_b32 s7, s15, 13
	s_lshl_b32 s9, s23, 12
	s_add_u32 s36, s24, 0x80
	s_addc_u32 s10, s25, 0
	s_add_i32 s81, s71, 0x18000
	s_and_b32 s37, s10, 0xffff
	s_mov_b32 s38, s18
	s_mov_b32 s39, s19
	s_mov_b32 m0, s81
	s_add_i32 s82, s71, 0x1a000
	s_waitcnt vmcnt(4)
	s_barrier
	buffer_load_dwordx4 v135, s[36:39], 0 offen lds
	s_mov_b32 m0, s82
	v_and_b32_e32 v0, 15, v2
	buffer_load_dwordx4 v137, s[36:39], 0 offen lds
	s_add_u32 s36, s26, 0x80
	s_addc_u32 s10, s27, 0
	s_and_b32 s37, s10, 0xffff
	s_add_i32 s83, s71, 0x8000
	s_add_i32 s84, s71, 0xa000
	s_mov_b32 m0, s83
	buffer_load_dwordx4 v134, s[36:39], 0 offen lds
	s_mov_b32 m0, s84
	s_add_i32 s85, s71, 0x1c000
	buffer_load_dwordx4 v136, s[36:39], 0 offen lds
	s_add_i32 s86, s71, 0x1e000
	s_add_u32 s16, s26, s0
	s_addc_u32 s8, s27, s1
	s_add_u32 s16, s16, 0x80
	s_addc_u32 s8, s8, 0
	s_and_b32 s17, s8, 0xffff
	s_add_i32 s88, s71, 0xc000
	s_add_i32 s89, s71, 0xe000
	s_mov_b32 m0, s88
	v_or_b32_e32 v138, s28, v0
	buffer_load_dwordx4 v134, s[16:19], 0 offen lds
	s_mov_b32 m0, s89
	s_nop 0
	buffer_load_dwordx4 v136, s[16:19], 0 offen lds
	v_and_b32_e32 v2, 48, v2
	v_lshlrev_b32_e32 v6, 6, v138
	s_movk_i32 s8, 0x3c0
	v_lshlrev_b32_e32 v7, 2, v138
	v_and_or_b32 v6, v6, s8, v2
	v_and_b32_e32 v7, 32, v7
	s_cmp_gt_i32 s6, 63
	v_bitop3_b32 v6, v6, s7, v7 bitop3:0xde
	v_lshlrev_b32_e32 v7, 2, v0
	s_cselect_b64 s[68:69], -1, 0
	s_lshl_b32 s6, s15, 12
	s_lshl_b32 s91, s22, 3
	v_lshl_or_b32 v2, v0, 6, v2
	v_and_b32_e32 v8, 32, v7
	s_lshl_b32 s7, s23, 10
	s_add_i32 s6, s6, 0
	s_abs_i32 s92, s91
	v_bitop3_b32 v8, v2, s9, v8 bitop3:0xde
	s_add_i32 s6, s6, s7
	v_and_b32_e32 v2, 0xc00, v4
	v_cvt_f32_u32_e32 v4, s92
	v_lshrrev_b32_e32 v1, 4, v3
	s_add_i32 s6, s6, 0x20040
	v_lshl_add_u32 v10, v1, 8, s6
	v_lshlrev_b32_e32 v11, 4, v0
	v_add_u32_e32 v139, s6, v7
	v_cmp_eq_u32_e64 s[6:7], 0, v0
	v_cmp_lt_u32_e64 s[8:9], 1, v0
	v_add_u32_e32 v110, 2, v0
	v_add_u32_e32 v112, 4, v0
	v_cmp_lt_u32_e64 s[10:11], 13, v0
	v_add_u32_e32 v114, -14, v0
	v_mov_b32_e32 v0, 0x7fffff00
	v_lshl_add_u32 v0, v3, 3, v0
	v_cmp_gt_u32_e32 vcc, 24, v3
	v_and_b32_e32 v108, 0x7fffff80, v0
	v_readlane_b32 s48, v252, 22
	v_cndmask_b32_e32 v2, 0, v2, vcc
	v_rcp_iflag_f32_e32 v4, v4
	v_lshlrev_b32_e32 v9, 2, v1
	v_mul_i32_i24_e32 v12, 0xffffff10, v1
	v_lshl_add_u64 v[0:1], v[108:109], 2, s[12:13]
	v_lshlrev_b32_e32 v108, 2, v2
	v_readlane_b32 s60, v252, 34
	v_readlane_b32 s61, v252, 35
	s_ashr_i32 s29, s28, 31
	s_lshl_b32 s46, s23, 6
	v_lshl_add_u64 v[2:3], s[60:61], 0, v[108:109]
	v_lshl_add_u64 v[0:1], s[28:29], 2, v[0:1]
	v_lshl_add_u64 v[2:3], v[2:3], 0, s[46:47]
	v_cndmask_b32_e64 v117, v1, v3, s[4:5]
	v_mul_f32_e32 v1, 0x4f7ffffe, v4
	v_cvt_u32_f32_e32 v1, v1
	s_sub_i32 s12, 0, s92
	s_waitcnt vmcnt(6)
	v_cndmask_b32_e64 v116, v0, v2, s[4:5]
	v_readfirstlane_b32 s13, v1
	v_cndmask_b32_e64 v0, 60, 12, s[4:5]
	s_mul_i32 s12, s12, s13
	v_and_b32_e32 v0, v0, v5
	s_mul_hi_u32 s12, s13, s12
	v_add_u32_e32 v1, 0, v8
	s_add_i32 s87, s80, -2
	s_add_i32 s88, s71, 0xc000
	v_mov_b32_e32 v111, v109
	v_mov_b32_e32 v113, v109
	v_mov_b32_e32 v115, v109
	s_add_i32 s89, s71, 0xe000
	s_ashr_i32 s90, s2, 31
	v_readlane_b32 s52, v252, 26
	v_readlane_b32 s58, v252, 32
	v_lshl_or_b32 v140, s23, 4, v9
	s_bfe_i32 s46, s22, 0x1001c
	s_add_i32 s93, s13, s12
	v_mov_b64_e32 v[118:119], 0x800
	v_mov_b64_e32 v[120:121], 0x7ff
	v_add_u32_e32 v141, 0x10000, v1
	v_add_u32_e32 v142, 0, v6
	v_add_u32_e32 v143, 0x14000, v1
	v_add_u32_e32 v144, 0x18000, v1
	v_add_u32_e32 v145, 0x1c000, v1
	v_add_u32_e32 v146, v10, v11
	v_add_u32_e32 v147, v10, v12
	v_mov_b32_e32 v148, 0x358637bd
	v_lshlrev_b32_e32 v108, 2, v0
	s_barrier
	v_readlane_b32 s49, v252, 23
	v_readlane_b32 s50, v252, 24
	v_readlane_b32 s51, v252, 25
	v_readlane_b32 s53, v252, 27
	v_readlane_b32 s54, v252, 28
	v_readlane_b32 s55, v252, 29
	v_readlane_b32 s56, v252, 30
	v_readlane_b32 s57, v252, 31
	v_readlane_b32 s59, v252, 33
	v_readlane_b32 s62, v252, 36
	v_readlane_b32 s63, v252, 37
	s_branch .LBB0_836

; #define PG8_STAGE(bufoff, gbase, voff) do { const __amdgpu_buffer_rsrc_t _r = __builtin_amdgcn_make_buffer_rsrc((void*)(gbase), (short)0, 0x7fffffff, 0x00020000); _Pragma("unroll") for (int _i = 0; _i < 2; ++_i) \
;         __builtin_amdgcn_raw_ptr_buffer_load_lds(_r, (LAS unsigned*)(lds + (bufoff) + ldsw + _i * 8192), 16, (int)(voff)[_i], 0, 0, 0); } while (0)
; #define PG8_LDA(dst, b, h) do { _Pragma("unroll") for (int m = 0; m < 4; ++m) _Pragma("unroll") for (int k = 0; k < 2; ++k) dst[m][k] = *(const LAS bf16x8*)(lds + PG8_SA(b, h) + aoff + m * 2048 + k * 1024); } while (0)
; #define PG8_WAIT_V(n) asm volatile("s_waitcnt vmcnt(" #n ")" ::: "memory")
; #define PG8_WAIT_L(n) asm volatile("s_waitcnt lgkmcnt(" #n ")" ::: "memory")
; #define PG8_BAR __builtin_amdgcn_s_barrier()
;     ...
;         for (int t = 0; t < nt; t += 2) {
;             const bool last = (t == nt - 2);
;             const char* a1 = cA + (size_t)(t + 1) * kstep;
;             const char* a2 = last ? nA : cA + (size_t)(t + 2) * kstep; const char* b2 = last ? nB : cB + (size_t)(t + 2) * kstep;
;             const char* a3 = a2 + kstep; const char* b3 = b2 + kstep;
;             PG8_LDB(B0, 0, 0); PG8_SCHED; PG8_LDA(At, 0, 0); PG8_STAGE(PG8_SA(1, 1), a1 + hstepA, voffA);
;             PG8_WAIT_L(8); PG8_BAR; PG8_WAIT_L(0); PG8_MMA(0, 0, At, B0); PG8_BAR; PG8_SCHED;
;             PG8_LDB(B1, 0, 1); PG8_STAGE(PG8_SB(0, 0), b2, voffB);
;             PG8_BAR; PG8_WAIT_L(0); PG8_MMA(0, 1, At, B1); PG8_BAR;
;             PG8_LDA(At, 0, 1); PG8_STAGE(PG8_SA(0, 0), a2, voffA);
;             PG8_BAR; PG8_WAIT_L(0); PG8_MMA(1, 0, At, B0); PG8_BAR; PG8_SCHED;
;             PG8_STAGE(PG8_SB(0, 1), b2 + hstepB, voffB);
;             PG8_WAIT_V(6); PG8_BAR; PG8_MMA(1, 1, At, B1); PG8_BAR;
;             PG8_LDB(B0, 1, 0); PG8_SCHED; PG8_LDA(At, 1, 0); PG8_STAGE(PG8_SA(0, 1), a2 + hstepA, voffA);
;             PG8_WAIT_L(8); PG8_BAR; PG8_WAIT_L(0); PG8_MMA(0, 0, At, B0); PG8_BAR; PG8_SCHED;
;             PG8_LDB(B1, 1, 1); PG8_STAGE(PG8_SB(1, 0), b3, voffB);
;             PG8_BAR; PG8_WAIT_L(0); PG8_MMA(0, 1, At, B1); PG8_BAR;
;             PG8_LDA(At, 1, 1); PG8_STAGE(PG8_SA(1, 0), a3, voffA);
;             PG8_BAR; PG8_WAIT_L(0); PG8_MMA(1, 0, At, B0); PG8_BAR; PG8_SCHED;
;             PG8_STAGE(PG8_SB(1, 1), b3 + hstepB, voffB);
;             PG8_WAIT_V(6); PG8_BAR; PG8_MMA(1, 1, At, B1); PG8_BAR;
.Lnext_done_23079:
.LBB0_842:
	s_ashr_i32 s59, s58, 31
	s_lshl_b64 s[16:17], s[58:59], 19
	s_add_u32 s64, s20, s16
	s_addc_u32 s65, s21, s17
	s_ashr_i32 s53, s52, 31
	s_lshl_b64 s[16:17], s[52:53], 19
	s_add_u32 s66, s33, s16
	v_cmp_lt_i64_e64 s[12:13], s[12:13], v[118:119]
	s_addc_u32 s67, s35, s17
	s_andn2_b64 vcc, exec, s[68:69]
	s_cbranch_vccnz .Lkzero_844
	s_and_b64 s[16:17], s[12:13], exec
	s_cselect_b32 s22, s65, s27
	s_cselect_b32 s23, s64, s26
	s_cselect_b32 s53, s67, s25
	s_cselect_b32 s59, s66, s24
	s_add_u32 s94, s26, 0x100
	s_addc_u32 s95, s27, 0
	s_add_u32 s96, s24, 0x100
	s_addc_u32 s97, s25, 0
	s_mov_b32 s16, 0
	ds_read_b128 v[100:103], v141
	ds_read_b128 v[104:107], v141 offset:1024
	ds_read_b128 v[122:125], v141 offset:2048
	ds_read_b128 v[126:129], v141 offset:3072
	s_add_i32 vcc_lo, s16, 2
	s_cmp_eq_u32 s87, s16
	s_cselect_b32 s36, s23, s94
	s_cselect_b32 s26, s22, s95
	s_cselect_b32 s27, s53, s97
	s_cselect_b32 s28, s59, s96
	s_add_u32 s24, s36, 0x80
	s_addc_u32 s25, s26, 0
	s_add_u32 s16, s96, s44
	s_addc_u32 s17, s97, s45
	s_add_u32 s16, s16, 0xffffff80
	s_addc_u32 s17, s17, -1
	s_and_b32 s17, s17, 0xffff
	s_mov_b32 m0, s85
	ds_read_b128 v[130:133], v142
	ds_read_b128 v[150:153], v142 offset:1024
	ds_read_b128 v[154:157], v142 offset:2048
	ds_read_b128 v[158:161], v142 offset:3072
	ds_read_b128 v[162:165], v142 offset:4096
	ds_read_b128 v[166:169], v142 offset:5120
	ds_read_b128 v[170:173], v142 offset:6144
	ds_read_b128 v[174:177], v142 offset:7168
	buffer_load_dwordx4 v222, s[16:19], 0 offen lds
	s_mov_b32 m0, s86
	s_nop 0
	buffer_load_dwordx4 v223, s[16:19], 0 offen lds
	s_waitcnt lgkmcnt(8)
	s_barrier
	s_waitcnt lgkmcnt(0)
	s_setprio 1
	v_mfma_f32_16x16x32_bf16 v[88:91], v[100:103], v[130:133], 0
	v_mfma_f32_16x16x32_bf16 v[96:99], v[122:125], v[130:133], 0
	v_mfma_f32_16x16x32_bf16 v[76:79], v[100:103], v[154:157], 0
	v_mfma_f32_16x16x32_bf16 v[84:87], v[122:125], v[154:157], 0
	v_mfma_f32_16x16x32_bf16 v[64:67], v[100:103], v[162:165], 0
	v_mfma_f32_16x16x32_bf16 v[72:75], v[122:125], v[162:165], 0
	v_mfma_f32_16x16x32_bf16 v[52:55], v[100:103], v[170:173], 0
	v_mfma_f32_16x16x32_bf16 v[60:63], v[122:125], v[170:173], 0
	v_mfma_f32_16x16x32_bf16 v[88:91], v[104:107], v[150:153], v[88:91]
	v_mfma_f32_16x16x32_bf16 v[96:99], v[126:129], v[150:153], v[96:99]
	v_mfma_f32_16x16x32_bf16 v[76:79], v[104:107], v[158:161], v[76:79]
	v_mfma_f32_16x16x32_bf16 v[84:87], v[126:129], v[158:161], v[84:87]
	v_mfma_f32_16x16x32_bf16 v[64:67], v[104:107], v[166:169], v[64:67]
	v_mfma_f32_16x16x32_bf16 v[72:75], v[126:129], v[166:169], v[72:75]
	v_mfma_f32_16x16x32_bf16 v[52:55], v[104:107], v[174:177], v[52:55]
	v_mfma_f32_16x16x32_bf16 v[60:63], v[126:129], v[174:177], v[60:63]
	s_setprio 0
	s_barrier
	s_and_b32 s29, s27, 0xffff
	s_mov_b32 s30, s18
	s_mov_b32 s31, s19
	s_mov_b32 m0, s73
	ds_read_b128 v[188:191], v142 offset:16384
	ds_read_b128 v[192:195], v142 offset:17408
	ds_read_b128 v[196:199], v142 offset:18432
	ds_read_b128 v[200:203], v142 offset:19456
	ds_read_b128 v[204:207], v142 offset:20480
	ds_read_b128 v[208:211], v142 offset:21504
	ds_read_b128 v[212:215], v142 offset:22528
	ds_read_b128 v[216:219], v142 offset:23552
	ds_read_b128 v[178:181], v143
	ds_read_b128 v[182:185], v143 offset:1024
	buffer_load_dwordx4 v135, s[28:31], 0 offen lds
	s_mov_b32 m0, s74
	s_nop 0
	buffer_load_dwordx4 v137, s[28:31], 0 offen lds
	s_waitcnt lgkmcnt(2)
	s_barrier
	s_waitcnt lgkmcnt(0)
	s_setprio 1
	v_mfma_f32_16x16x32_bf16 v[44:47], v[100:103], v[188:191], 0
	v_mfma_f32_16x16x32_bf16 v[48:51], v[122:125], v[188:191], 0
	v_mfma_f32_16x16x32_bf16 v[28:31], v[100:103], v[196:199], 0
	v_mfma_f32_16x16x32_bf16 v[36:39], v[122:125], v[196:199], 0
	v_mfma_f32_16x16x32_bf16 v[12:15], v[100:103], v[204:207], 0
	v_mfma_f32_16x16x32_bf16 v[20:23], v[122:125], v[204:207], 0
	v_mfma_f32_16x16x32_bf16 v[0:3], v[100:103], v[212:215], 0
	v_mfma_f32_16x16x32_bf16 v[8:11], v[122:125], v[212:215], 0
	v_mfma_f32_16x16x32_bf16 v[44:47], v[104:107], v[192:195], v[44:47]
	v_mfma_f32_16x16x32_bf16 v[48:51], v[126:129], v[192:195], v[48:51]
	v_mfma_f32_16x16x32_bf16 v[28:31], v[104:107], v[200:203], v[28:31]
	v_mfma_f32_16x16x32_bf16 v[36:39], v[126:129], v[200:203], v[36:39]
	v_mfma_f32_16x16x32_bf16 v[12:15], v[104:107], v[208:211], v[12:15]
	v_mfma_f32_16x16x32_bf16 v[20:23], v[126:129], v[208:211], v[20:23]
	v_mfma_f32_16x16x32_bf16 v[0:3], v[104:107], v[216:219], v[0:3]
	v_mfma_f32_16x16x32_bf16 v[8:11], v[126:129], v[216:219], v[8:11]
	s_setprio 0
	s_barrier
	s_and_b32 s37, s26, 0xffff
	s_mov_b32 s38, s18
	s_mov_b32 s39, s19
	s_mov_b32 m0, s71
	s_nop 0
	buffer_load_dwordx4 v134, s[36:39], 0 offen lds
	s_mov_b32 m0, s75
	s_nop 0
	buffer_load_dwordx4 v136, s[36:39], 0 offen lds
	s_add_u32 s36, s36, s0
	s_addc_u32 s17, s26, s1
	s_and_b32 s37, s17, 0xffff
	s_mov_b32 m0, s78
	s_nop 0
	buffer_load_dwordx4 v134, s[36:39], 0 offen lds
	s_mov_b32 m0, s79
	s_nop 0
	buffer_load_dwordx4 v136, s[36:39], 0 offen lds
	s_waitcnt vmcnt(6)
	s_barrier
	s_setprio 1
	v_mfma_f32_16x16x32_bf16 v[92:95], v[178:181], v[130:133], 0
	v_mfma_f32_16x16x32_bf16 v[80:83], v[178:181], v[154:157], 0
	v_mfma_f32_16x16x32_bf16 v[68:71], v[178:181], v[162:165], 0
	v_mfma_f32_16x16x32_bf16 v[56:59], v[178:181], v[170:173], 0
	v_mfma_f32_16x16x32_bf16 v[40:43], v[178:181], v[188:191], 0
	v_mfma_f32_16x16x32_bf16 v[32:35], v[178:181], v[196:199], 0
	v_mfma_f32_16x16x32_bf16 v[16:19], v[178:181], v[204:207], 0
	v_mfma_f32_16x16x32_bf16 v[4:7], v[178:181], v[212:215], 0
	v_mfma_f32_16x16x32_bf16 v[92:95], v[182:185], v[150:153], v[92:95]
	v_mfma_f32_16x16x32_bf16 v[80:83], v[182:185], v[158:161], v[80:83]
	v_mfma_f32_16x16x32_bf16 v[68:71], v[182:185], v[166:169], v[68:71]
	v_mfma_f32_16x16x32_bf16 v[56:59], v[182:185], v[174:177], v[56:59]
	v_mfma_f32_16x16x32_bf16 v[40:43], v[182:185], v[192:195], v[40:43]
	v_mfma_f32_16x16x32_bf16 v[32:35], v[182:185], v[200:203], v[32:35]
	v_mfma_f32_16x16x32_bf16 v[16:19], v[182:185], v[208:211], v[16:19]
	v_mfma_f32_16x16x32_bf16 v[4:7], v[182:185], v[216:219], v[4:7]
	s_setprio 0
	s_barrier
	s_branch .Lkmid_844
; #define PG8_STAGE(bufoff, gbase, voff) do { const __amdgpu_buffer_rsrc_t _r = __builtin_amdgcn_make_buffer_rsrc((void*)(gbase), (short)0, 0x7fffffff, 0x00020000); _Pragma("unroll") for (int _i = 0; _i < 2; ++_i) \
;         __builtin_amdgcn_raw_ptr_buffer_load_lds(_r, (LAS unsigned*)(lds + (bufoff) + ldsw + _i * 8192), 16, (int)(voff)[_i], 0, 0, 0); } while (0)
; #define PG8_LDA(dst, b, h) do { _Pragma("unroll") for (int m = 0; m < 4; ++m) _Pragma("unroll") for (int k = 0; k < 2; ++k) dst[m][k] = *(const LAS bf16x8*)(lds + PG8_SA(b, h) + aoff + m * 2048 + k * 1024); } while (0)
; #define PG8_LDB(dst, b, h) do { _Pragma("unroll") for (int n = 0; n < 2; ++n) _Pragma("unroll") for (int k = 0; k < 2; ++k) dst[n][k] = *(const LAS bf16x8*)(lds + PG8_SB(b, h) + boff + n * 2048 + k * 1024); } while (0)
; #define PG8_MMA(ai, bj, At, Bt) do { __builtin_amdgcn_s_setprio(1); _Pragma("unroll") for (int k = 0; k < 2; ++k) _Pragma("unroll") for (int m = 0; m < 4; ++m) _Pragma("unroll") for (int n = 0; n < ((bj) == 1 ? NB1 : 2); ++n) \
;         acc[ai][bj][m][n] = __builtin_amdgcn_mfma_f32_16x16x32_bf16(Bt[n][k], At[m][k], acc[ai][bj][m][n], 0, 0, 0); __builtin_amdgcn_s_setprio(0); } while (0)
; #define PG8_WAIT_V(n) asm volatile("s_waitcnt vmcnt(" #n ")" ::: "memory")
; #define PG8_WAIT_L(n) asm volatile("s_waitcnt lgkmcnt(" #n ")" ::: "memory")
; #define PG8_BAR __builtin_amdgcn_s_barrier()
; #define PG8_SCHED __builtin_amdgcn_sched_barrier(0)
;     ...
;             PG8_LDB(B0, 0, 0); PG8_SCHED; PG8_LDA(At, 0, 0); PG8_STAGE(PG8_SA(1, 1), a1 + hstepA, voffA);
;             PG8_WAIT_L(8); PG8_BAR; PG8_WAIT_L(0); PG8_MMA(0, 0, At, B0); PG8_BAR; PG8_SCHED;
;             PG8_LDB(B1, 0, 1); PG8_STAGE(PG8_SB(0, 0), b2, voffB);
;             PG8_BAR; PG8_WAIT_L(0); PG8_MMA(0, 1, At, B1); PG8_BAR;
;             PG8_LDA(At, 0, 1); PG8_STAGE(PG8_SA(0, 0), a2, voffA);
;             PG8_BAR; PG8_WAIT_L(0); PG8_MMA(1, 0, At, B0); PG8_BAR; PG8_SCHED;
;             PG8_STAGE(PG8_SB(0, 1), b2 + hstepB, voffB);
;             PG8_WAIT_V(6); PG8_BAR; PG8_MMA(1, 1, At, B1); PG8_BAR;
.LBB0_844:
	ds_read_b128 v[100:103], v141
	ds_read_b128 v[104:107], v141 offset:1024
	ds_read_b128 v[122:125], v141 offset:2048
	ds_read_b128 v[126:129], v141 offset:3072
	s_add_i32 vcc_lo, s16, 2
	s_cmp_eq_u32 s87, s16
	s_cselect_b32 s36, s23, s94
	s_cselect_b32 s26, s22, s95
	s_cselect_b32 s27, s53, s97
	s_cselect_b32 s28, s59, s96
	s_add_u32 s24, s36, 0x80
	s_addc_u32 s25, s26, 0
	s_add_u32 s16, s96, s44
	s_addc_u32 s17, s97, s45
	s_add_u32 s16, s16, 0xffffff80
	s_addc_u32 s17, s17, -1
	s_and_b32 s17, s17, 0xffff
	s_mov_b32 m0, s85
	ds_read_b128 v[130:133], v142
	ds_read_b128 v[150:153], v142 offset:1024
	ds_read_b128 v[154:157], v142 offset:2048
	ds_read_b128 v[158:161], v142 offset:3072
	ds_read_b128 v[162:165], v142 offset:4096
	ds_read_b128 v[166:169], v142 offset:5120
	ds_read_b128 v[170:173], v142 offset:6144
	ds_read_b128 v[174:177], v142 offset:7168
	buffer_load_dwordx4 v222, s[16:19], 0 offen lds
	s_mov_b32 m0, s86
	s_nop 0
	buffer_load_dwordx4 v223, s[16:19], 0 offen lds
	s_waitcnt lgkmcnt(8)
	s_barrier
	s_waitcnt lgkmcnt(0)
	s_setprio 1
	v_mfma_f32_16x16x32_bf16 v[88:91], v[100:103], v[130:133], v[88:91]
	v_mfma_f32_16x16x32_bf16 v[96:99], v[122:125], v[130:133], v[96:99]
	v_mfma_f32_16x16x32_bf16 v[76:79], v[100:103], v[154:157], v[76:79]
	v_mfma_f32_16x16x32_bf16 v[84:87], v[122:125], v[154:157], v[84:87]
	v_mfma_f32_16x16x32_bf16 v[64:67], v[100:103], v[162:165], v[64:67]
	v_mfma_f32_16x16x32_bf16 v[72:75], v[122:125], v[162:165], v[72:75]
	v_mfma_f32_16x16x32_bf16 v[52:55], v[100:103], v[170:173], v[52:55]
	v_mfma_f32_16x16x32_bf16 v[60:63], v[122:125], v[170:173], v[60:63]
	v_mfma_f32_16x16x32_bf16 v[88:91], v[104:107], v[150:153], v[88:91]
	v_mfma_f32_16x16x32_bf16 v[96:99], v[126:129], v[150:153], v[96:99]
	v_mfma_f32_16x16x32_bf16 v[76:79], v[104:107], v[158:161], v[76:79]
	v_mfma_f32_16x16x32_bf16 v[84:87], v[126:129], v[158:161], v[84:87]
	v_mfma_f32_16x16x32_bf16 v[64:67], v[104:107], v[166:169], v[64:67]
	v_mfma_f32_16x16x32_bf16 v[72:75], v[126:129], v[166:169], v[72:75]
	v_mfma_f32_16x16x32_bf16 v[52:55], v[104:107], v[174:177], v[52:55]
	v_mfma_f32_16x16x32_bf16 v[60:63], v[126:129], v[174:177], v[60:63]
	s_setprio 0
	s_barrier
	s_and_b32 s29, s27, 0xffff
	s_mov_b32 s30, s18
	s_mov_b32 s31, s19
	s_mov_b32 m0, s73
	ds_read_b128 v[188:191], v142 offset:16384
	ds_read_b128 v[192:195], v142 offset:17408
	ds_read_b128 v[196:199], v142 offset:18432
	ds_read_b128 v[200:203], v142 offset:19456
	ds_read_b128 v[204:207], v142 offset:20480
	ds_read_b128 v[208:211], v142 offset:21504
	ds_read_b128 v[212:215], v142 offset:22528
	ds_read_b128 v[216:219], v142 offset:23552
	ds_read_b128 v[178:181], v143
	ds_read_b128 v[182:185], v143 offset:1024
	buffer_load_dwordx4 v135, s[28:31], 0 offen lds
	s_mov_b32 m0, s74
	s_nop 0
	buffer_load_dwordx4 v137, s[28:31], 0 offen lds
	s_waitcnt lgkmcnt(2)
	s_barrier
	s_waitcnt lgkmcnt(0)
	s_setprio 1
	v_mfma_f32_16x16x32_bf16 v[44:47], v[100:103], v[188:191], v[44:47]
	v_mfma_f32_16x16x32_bf16 v[48:51], v[122:125], v[188:191], v[48:51]
	v_mfma_f32_16x16x32_bf16 v[28:31], v[100:103], v[196:199], v[28:31]
	v_mfma_f32_16x16x32_bf16 v[36:39], v[122:125], v[196:199], v[36:39]
	v_mfma_f32_16x16x32_bf16 v[12:15], v[100:103], v[204:207], v[12:15]
	v_mfma_f32_16x16x32_bf16 v[20:23], v[122:125], v[204:207], v[20:23]
	v_mfma_f32_16x16x32_bf16 v[0:3], v[100:103], v[212:215], v[0:3]
	v_mfma_f32_16x16x32_bf16 v[8:11], v[122:125], v[212:215], v[8:11]
	v_mfma_f32_16x16x32_bf16 v[44:47], v[104:107], v[192:195], v[44:47]
	v_mfma_f32_16x16x32_bf16 v[48:51], v[126:129], v[192:195], v[48:51]
	v_mfma_f32_16x16x32_bf16 v[28:31], v[104:107], v[200:203], v[28:31]
	v_mfma_f32_16x16x32_bf16 v[36:39], v[126:129], v[200:203], v[36:39]
	v_mfma_f32_16x16x32_bf16 v[12:15], v[104:107], v[208:211], v[12:15]
	v_mfma_f32_16x16x32_bf16 v[20:23], v[126:129], v[208:211], v[20:23]
	v_mfma_f32_16x16x32_bf16 v[0:3], v[104:107], v[216:219], v[0:3]
	v_mfma_f32_16x16x32_bf16 v[8:11], v[126:129], v[216:219], v[8:11]
	s_setprio 0
	s_barrier
	s_and_b32 s37, s26, 0xffff
	s_mov_b32 s38, s18
	s_mov_b32 s39, s19
	s_mov_b32 m0, s71
	s_nop 0
	buffer_load_dwordx4 v134, s[36:39], 0 offen lds
	s_mov_b32 m0, s75
	s_nop 0
	buffer_load_dwordx4 v136, s[36:39], 0 offen lds
	s_add_u32 s36, s36, s0
	s_addc_u32 s17, s26, s1
	s_and_b32 s37, s17, 0xffff
	s_mov_b32 m0, s78
	s_nop 0
	buffer_load_dwordx4 v134, s[36:39], 0 offen lds
	s_mov_b32 m0, s79
	s_nop 0
	buffer_load_dwordx4 v136, s[36:39], 0 offen lds
	s_waitcnt vmcnt(6)
	s_barrier
	s_setprio 1
	v_mfma_f32_16x16x32_bf16 v[92:95], v[178:181], v[130:133], v[92:95]
	v_mfma_f32_16x16x32_bf16 v[80:83], v[178:181], v[154:157], v[80:83]
	v_mfma_f32_16x16x32_bf16 v[68:71], v[178:181], v[162:165], v[68:71]
	v_mfma_f32_16x16x32_bf16 v[56:59], v[178:181], v[170:173], v[56:59]
	v_mfma_f32_16x16x32_bf16 v[40:43], v[178:181], v[188:191], v[40:43]
	v_mfma_f32_16x16x32_bf16 v[32:35], v[178:181], v[196:199], v[32:35]
	v_mfma_f32_16x16x32_bf16 v[16:19], v[178:181], v[204:207], v[16:19]
	v_mfma_f32_16x16x32_bf16 v[4:7], v[178:181], v[212:215], v[4:7]
	v_mfma_f32_16x16x32_bf16 v[92:95], v[182:185], v[150:153], v[92:95]
	v_mfma_f32_16x16x32_bf16 v[80:83], v[182:185], v[158:161], v[80:83]
	v_mfma_f32_16x16x32_bf16 v[68:71], v[182:185], v[166:169], v[68:71]
	v_mfma_f32_16x16x32_bf16 v[56:59], v[182:185], v[174:177], v[56:59]
	v_mfma_f32_16x16x32_bf16 v[40:43], v[182:185], v[192:195], v[40:43]
	v_mfma_f32_16x16x32_bf16 v[32:35], v[182:185], v[200:203], v[32:35]
	v_mfma_f32_16x16x32_bf16 v[16:19], v[182:185], v[208:211], v[16:19]
	v_mfma_f32_16x16x32_bf16 v[4:7], v[182:185], v[216:219], v[4:7]
	s_setprio 0
	s_barrier
; #define PG8_STAGE(bufoff, gbase, voff) do { const __amdgpu_buffer_rsrc_t _r = __builtin_amdgcn_make_buffer_rsrc((void*)(gbase), (short)0, 0x7fffffff, 0x00020000); _Pragma("unroll") for (int _i = 0; _i < 2; ++_i) \
;         __builtin_amdgcn_raw_ptr_buffer_load_lds(_r, (LAS unsigned*)(lds + (bufoff) + ldsw + _i * 8192), 16, (int)(voff)[_i], 0, 0, 0); } while (0)
; #define PG8_LDA(dst, b, h) do { _Pragma("unroll") for (int m = 0; m < 4; ++m) _Pragma("unroll") for (int k = 0; k < 2; ++k) dst[m][k] = *(const LAS bf16x8*)(lds + PG8_SA(b, h) + aoff + m * 2048 + k * 1024); } while (0)
; #define PG8_LDB(dst, b, h) do { _Pragma("unroll") for (int n = 0; n < 2; ++n) _Pragma("unroll") for (int k = 0; k < 2; ++k) dst[n][k] = *(const LAS bf16x8*)(lds + PG8_SB(b, h) + boff + n * 2048 + k * 1024); } while (0)
; #define PG8_MMA(ai, bj, At, Bt) do { __builtin_amdgcn_s_setprio(1); _Pragma("unroll") for (int k = 0; k < 2; ++k) _Pragma("unroll") for (int m = 0; m < 4; ++m) _Pragma("unroll") for (int n = 0; n < ((bj) == 1 ? NB1 : 2); ++n) \
;         acc[ai][bj][m][n] = __builtin_amdgcn_mfma_f32_16x16x32_bf16(Bt[n][k], At[m][k], acc[ai][bj][m][n], 0, 0, 0); __builtin_amdgcn_s_setprio(0); } while (0)
; #define PG8_WAIT_V(n) asm volatile("s_waitcnt vmcnt(" #n ")" ::: "memory")
; #define PG8_WAIT_L(n) asm volatile("s_waitcnt lgkmcnt(" #n ")" ::: "memory")
; #define PG8_BAR __builtin_amdgcn_s_barrier()
; #define PG8_SCHED __builtin_amdgcn_sched_barrier(0)
;     ...
;             PG8_LDB(B0, 1, 0); PG8_SCHED; PG8_LDA(At, 1, 0); PG8_STAGE(PG8_SA(0, 1), a2 + hstepA, voffA);
;             PG8_WAIT_L(8); PG8_BAR; PG8_WAIT_L(0); PG8_MMA(0, 0, At, B0); PG8_BAR; PG8_SCHED;
;             PG8_LDB(B1, 1, 1); PG8_STAGE(PG8_SB(1, 0), b3, voffB);
;             PG8_BAR; PG8_WAIT_L(0); PG8_MMA(0, 1, At, B1); PG8_BAR;
;             PG8_LDA(At, 1, 1); PG8_STAGE(PG8_SA(1, 0), a3, voffA);
;             PG8_BAR; PG8_WAIT_L(0); PG8_MMA(1, 0, At, B0); PG8_BAR; PG8_SCHED;
;             PG8_STAGE(PG8_SB(1, 1), b3 + hstepB, voffB);
;             PG8_WAIT_V(6); PG8_BAR; PG8_MMA(1, 1, At, B1); PG8_BAR;
.Lkmid_844:
	ds_read_b128 v[100:103], v144
	ds_read_b128 v[104:107], v144 offset:1024
	ds_read_b128 v[122:125], v144 offset:2048
	ds_read_b128 v[126:129], v144 offset:3072
	s_add_u32 s16, s28, s44
	s_addc_u32 vcc_hi, s27, s45
	s_and_b32 s17, vcc_hi, 0xffff
	s_mov_b32 m0, s76
	ds_read_b128 v[130:133], v142 offset:32768
	ds_read_b128 v[150:153], v142 offset:33792
	ds_read_b128 v[154:157], v142 offset:34816
	ds_read_b128 v[158:161], v142 offset:35840
	ds_read_b128 v[162:165], v142 offset:36864
	ds_read_b128 v[166:169], v142 offset:37888
	ds_read_b128 v[170:173], v142 offset:38912
	ds_read_b128 v[174:177], v142 offset:39936
	buffer_load_dwordx4 v222, s[16:19], 0 offen lds
	s_mov_b32 m0, s77
	s_nop 0
	buffer_load_dwordx4 v223, s[16:19], 0 offen lds
	s_waitcnt lgkmcnt(8)
	s_barrier
	s_waitcnt lgkmcnt(0)
	s_setprio 1
	v_mfma_f32_16x16x32_bf16 v[88:91], v[100:103], v[130:133], v[88:91]
	v_mfma_f32_16x16x32_bf16 v[96:99], v[122:125], v[130:133], v[96:99]
	v_mfma_f32_16x16x32_bf16 v[76:79], v[100:103], v[154:157], v[76:79]
	v_mfma_f32_16x16x32_bf16 v[84:87], v[122:125], v[154:157], v[84:87]
	v_mfma_f32_16x16x32_bf16 v[64:67], v[100:103], v[162:165], v[64:67]
	v_mfma_f32_16x16x32_bf16 v[72:75], v[122:125], v[162:165], v[72:75]
	v_mfma_f32_16x16x32_bf16 v[52:55], v[100:103], v[170:173], v[52:55]
	v_mfma_f32_16x16x32_bf16 v[60:63], v[122:125], v[170:173], v[60:63]
	v_mfma_f32_16x16x32_bf16 v[88:91], v[104:107], v[150:153], v[88:91]
	v_mfma_f32_16x16x32_bf16 v[96:99], v[126:129], v[150:153], v[96:99]
	v_mfma_f32_16x16x32_bf16 v[76:79], v[104:107], v[158:161], v[76:79]
	v_mfma_f32_16x16x32_bf16 v[84:87], v[126:129], v[158:161], v[84:87]
	v_mfma_f32_16x16x32_bf16 v[64:67], v[104:107], v[166:169], v[64:67]
	v_mfma_f32_16x16x32_bf16 v[72:75], v[126:129], v[166:169], v[72:75]
	v_mfma_f32_16x16x32_bf16 v[52:55], v[104:107], v[174:177], v[52:55]
	v_mfma_f32_16x16x32_bf16 v[60:63], v[126:129], v[174:177], v[60:63]
	s_setprio 0
	s_barrier
	s_add_u32 s28, s28, 0x80
	s_addc_u32 s17, s27, 0
	s_and_b32 s29, s17, 0xffff
	s_mov_b32 m0, s81
	ds_read_b128 v[188:191], v142 offset:49152
	ds_read_b128 v[192:195], v142 offset:50176
	ds_read_b128 v[196:199], v142 offset:51200
	ds_read_b128 v[200:203], v142 offset:52224
	ds_read_b128 v[204:207], v142 offset:53248
	ds_read_b128 v[208:211], v142 offset:54272
	ds_read_b128 v[212:215], v142 offset:55296
	ds_read_b128 v[216:219], v142 offset:56320
	ds_read_b128 v[178:181], v145
	ds_read_b128 v[182:185], v145 offset:1024
	buffer_load_dwordx4 v135, s[28:31], 0 offen lds
	s_mov_b32 m0, s82
	s_nop 0
	buffer_load_dwordx4 v137, s[28:31], 0 offen lds
	s_waitcnt lgkmcnt(2)
	s_barrier
	s_waitcnt lgkmcnt(0)
	s_setprio 1
	v_mfma_f32_16x16x32_bf16 v[44:47], v[100:103], v[188:191], v[44:47]
	v_mfma_f32_16x16x32_bf16 v[48:51], v[122:125], v[188:191], v[48:51]
	v_mfma_f32_16x16x32_bf16 v[28:31], v[100:103], v[196:199], v[28:31]
	v_mfma_f32_16x16x32_bf16 v[36:39], v[122:125], v[196:199], v[36:39]
	v_mfma_f32_16x16x32_bf16 v[12:15], v[100:103], v[204:207], v[12:15]
	v_mfma_f32_16x16x32_bf16 v[20:23], v[122:125], v[204:207], v[20:23]
	v_mfma_f32_16x16x32_bf16 v[0:3], v[100:103], v[212:215], v[0:3]
	v_mfma_f32_16x16x32_bf16 v[8:11], v[122:125], v[212:215], v[8:11]
	v_mfma_f32_16x16x32_bf16 v[44:47], v[104:107], v[192:195], v[44:47]
	v_mfma_f32_16x16x32_bf16 v[48:51], v[126:129], v[192:195], v[48:51]
	v_mfma_f32_16x16x32_bf16 v[28:31], v[104:107], v[200:203], v[28:31]
	v_mfma_f32_16x16x32_bf16 v[36:39], v[126:129], v[200:203], v[36:39]
	v_mfma_f32_16x16x32_bf16 v[12:15], v[104:107], v[208:211], v[12:15]
	v_mfma_f32_16x16x32_bf16 v[20:23], v[126:129], v[208:211], v[20:23]
	v_mfma_f32_16x16x32_bf16 v[0:3], v[104:107], v[216:219], v[0:3]
	v_mfma_f32_16x16x32_bf16 v[8:11], v[126:129], v[216:219], v[8:11]
	s_setprio 0
	s_barrier
	s_and_b32 s25, s25, 0xffff
	s_mov_b32 s26, s18
	s_mov_b32 s27, s19
	s_mov_b32 m0, s83
	s_nop 0
	buffer_load_dwordx4 v134, s[24:27], 0 offen lds
	s_mov_b32 m0, s84
	s_nop 0
	buffer_load_dwordx4 v136, s[24:27], 0 offen lds
	s_add_u32 s24, s24, s0
	s_addc_u32 s25, s25, s1
	s_and_b32 s25, s25, 0xffff
	s_mov_b32 m0, s88
	s_nop 0
	buffer_load_dwordx4 v134, s[24:27], 0 offen lds
	s_mov_b32 m0, s89
	s_nop 0
	buffer_load_dwordx4 v136, s[24:27], 0 offen lds
	s_waitcnt vmcnt(6)
	s_barrier
	s_setprio 1
	v_mfma_f32_16x16x32_bf16 v[92:95], v[178:181], v[130:133], v[92:95]
	v_mfma_f32_16x16x32_bf16 v[80:83], v[178:181], v[154:157], v[80:83]
	v_mfma_f32_16x16x32_bf16 v[68:71], v[178:181], v[162:165], v[68:71]
	v_mfma_f32_16x16x32_bf16 v[56:59], v[178:181], v[170:173], v[56:59]
	v_mfma_f32_16x16x32_bf16 v[40:43], v[178:181], v[188:191], v[40:43]
	v_mfma_f32_16x16x32_bf16 v[32:35], v[178:181], v[196:199], v[32:35]
	v_mfma_f32_16x16x32_bf16 v[16:19], v[178:181], v[204:207], v[16:19]
	v_mfma_f32_16x16x32_bf16 v[4:7], v[178:181], v[212:215], v[4:7]
	v_mfma_f32_16x16x32_bf16 v[92:95], v[182:185], v[150:153], v[92:95]
	v_mfma_f32_16x16x32_bf16 v[80:83], v[182:185], v[158:161], v[80:83]
	v_mfma_f32_16x16x32_bf16 v[68:71], v[182:185], v[166:169], v[68:71]
	v_mfma_f32_16x16x32_bf16 v[56:59], v[182:185], v[174:177], v[56:59]
	v_mfma_f32_16x16x32_bf16 v[40:43], v[182:185], v[192:195], v[40:43]
	v_mfma_f32_16x16x32_bf16 v[32:35], v[182:185], v[200:203], v[32:35]
	v_mfma_f32_16x16x32_bf16 v[16:19], v[182:185], v[208:211], v[16:19]
	v_mfma_f32_16x16x32_bf16 v[4:7], v[182:185], v[216:219], v[4:7]
	s_setprio 0
	s_add_u32 s94, s94, 0x100
	s_addc_u32 s95, s95, 0
	s_add_u32 s96, s96, 0x100
	s_addc_u32 s97, s97, 0
	s_cmp_ge_i32 vcc_lo, s80
	s_mov_b32 s16, vcc_lo
	s_barrier
	s_cbranch_scc0 .LBB0_844
	v_readlane_b32 s96, v252, 38
	v_readlane_b32 s97, v252, 39
